# mLSTM passC: prefix-max via DPP scan, rs/qn row sums with batched LDS reads; NL scan 64 steps per trip
# speedup vs baseline: 1.0045x; 1.0045x over previous
.LBB0_708:
	v_lshl_add_u64 v[6:7], v[0:1], 0, s[0:1]
	v_add_co_u32_e32 v6, vcc, 0x3cb83000, v6
	s_mov_b64 s[98:99], 0x1000
	s_nop 0
	v_addc_co_u32_e32 v7, vcc, 0, v7, vcc
	v_lshl_add_u64 v[8:9], v[6:7], 0, s[98:99]
	v_lshl_add_u64 v[10:11], v[8:9], 0, s[98:99]
	v_lshl_add_u64 v[12:13], v[10:11], 0, s[98:99]
	v_lshl_add_u64 v[14:15], v[12:13], 0, s[98:99]
	v_lshl_add_u64 v[16:17], v[14:15], 0, s[98:99]
	v_lshl_add_u64 v[18:19], v[16:17], 0, s[98:99]
	v_lshl_add_u64 v[20:21], v[18:19], 0, s[98:99]
	global_load_dword v100, v[6:7], off
	global_load_dword v101, v[6:7], off offset:512
	global_load_dword v102, v[6:7], off offset:1024
	global_load_dword v103, v[6:7], off offset:1536
	global_load_dword v104, v[6:7], off offset:2048
	global_load_dword v105, v[6:7], off offset:2560
	global_load_dword v106, v[6:7], off offset:3072
	global_load_dword v107, v[6:7], off offset:3584
	global_load_dword v108, v[8:9], off
	global_load_dword v109, v[8:9], off offset:512
	global_load_dword v110, v[8:9], off offset:1024
	global_load_dword v111, v[8:9], off offset:1536
	global_load_dword v112, v[8:9], off offset:2048
	global_load_dword v113, v[8:9], off offset:2560
	global_load_dword v114, v[8:9], off offset:3072
	global_load_dword v115, v[8:9], off offset:3584
	global_load_dword v116, v[10:11], off
	global_load_dword v117, v[10:11], off offset:512
	global_load_dword v118, v[10:11], off offset:1024
	global_load_dword v119, v[10:11], off offset:1536
	global_load_dword v120, v[10:11], off offset:2048
	global_load_dword v121, v[10:11], off offset:2560
	global_load_dword v122, v[10:11], off offset:3072
	global_load_dword v123, v[10:11], off offset:3584
	global_load_dword v124, v[12:13], off
	global_load_dword v125, v[12:13], off offset:512
	global_load_dword v126, v[12:13], off offset:1024
	global_load_dword v127, v[12:13], off offset:1536
	global_load_dword v128, v[12:13], off offset:2048
	global_load_dword v129, v[12:13], off offset:2560
	global_load_dword v130, v[12:13], off offset:3072
	global_load_dword v131, v[12:13], off offset:3584
	global_load_dword v132, v[14:15], off
	global_load_dword v133, v[14:15], off offset:512
	global_load_dword v134, v[14:15], off offset:1024
	global_load_dword v135, v[14:15], off offset:1536
	global_load_dword v136, v[14:15], off offset:2048
	global_load_dword v137, v[14:15], off offset:2560
	global_load_dword v138, v[14:15], off offset:3072
	global_load_dword v139, v[14:15], off offset:3584
	global_load_dword v140, v[16:17], off
	global_load_dword v141, v[16:17], off offset:512
	global_load_dword v142, v[16:17], off offset:1024
	global_load_dword v143, v[16:17], off offset:1536
	global_load_dword v144, v[16:17], off offset:2048
	global_load_dword v145, v[16:17], off offset:2560
	global_load_dword v146, v[16:17], off offset:3072
	global_load_dword v147, v[16:17], off offset:3584
	global_load_dword v148, v[18:19], off
	global_load_dword v149, v[18:19], off offset:512
	global_load_dword v150, v[18:19], off offset:1024
	global_load_dword v151, v[18:19], off offset:1536
	global_load_dword v152, v[18:19], off offset:2048
	global_load_dword v153, v[18:19], off offset:2560
	global_load_dword v154, v[18:19], off offset:3072
	global_load_dword v155, v[18:19], off offset:3584
	global_load_dword v156, v[20:21], off
	global_load_dword v157, v[20:21], off offset:512
	global_load_dword v158, v[20:21], off offset:1024
	global_load_dword v159, v[20:21], off offset:1536
	global_load_dword v160, v[20:21], off offset:2048
	global_load_dword v161, v[20:21], off offset:2560
	global_load_dword v162, v[20:21], off offset:3072
	global_load_dword v163, v[20:21], off offset:3584
	global_load_dword v164, v[2:3], off offset:-4
	global_load_dword v165, v[2:3], off
	global_load_dword v166, v[2:3], off offset:4
	global_load_dword v167, v[2:3], off offset:8
	global_load_dword v168, v[2:3], off offset:12
	global_load_dword v169, v[2:3], off offset:16
	global_load_dword v170, v[2:3], off offset:20
	global_load_dword v171, v[2:3], off offset:24
	global_load_dword v172, v[2:3], off offset:28
	global_load_dword v173, v[2:3], off offset:32
	global_load_dword v174, v[2:3], off offset:36
	global_load_dword v175, v[2:3], off offset:40
	global_load_dword v176, v[2:3], off offset:44
	global_load_dword v177, v[2:3], off offset:48
	global_load_dword v178, v[2:3], off offset:52
	global_load_dword v179, v[2:3], off offset:56
	global_load_dword v180, v[2:3], off offset:60
	global_load_dword v181, v[2:3], off offset:64
	global_load_dword v182, v[2:3], off offset:68
	global_load_dword v183, v[2:3], off offset:72
	global_load_dword v184, v[2:3], off offset:76
	global_load_dword v185, v[2:3], off offset:80
	global_load_dword v186, v[2:3], off offset:84
	global_load_dword v187, v[2:3], off offset:88
	global_load_dword v188, v[2:3], off offset:92
	global_load_dword v189, v[2:3], off offset:96
	global_load_dword v190, v[2:3], off offset:100
	global_load_dword v191, v[2:3], off offset:104
	global_load_dword v192, v[2:3], off offset:108
	global_load_dword v193, v[2:3], off offset:112
	global_load_dword v194, v[2:3], off offset:116
	global_load_dword v195, v[2:3], off offset:120
	global_load_dword v196, v[2:3], off offset:124
	global_load_dword v197, v[2:3], off offset:128
	global_load_dword v198, v[2:3], off offset:132
	global_load_dword v199, v[2:3], off offset:136
	global_load_dword v200, v[2:3], off offset:140
	global_load_dword v201, v[2:3], off offset:144
	global_load_dword v202, v[2:3], off offset:148
	global_load_dword v203, v[2:3], off offset:152
	global_load_dword v204, v[2:3], off offset:156
	global_load_dword v205, v[2:3], off offset:160
	global_load_dword v206, v[2:3], off offset:164
	global_load_dword v207, v[2:3], off offset:168
	global_load_dword v208, v[2:3], off offset:172
	global_load_dword v209, v[2:3], off offset:176
	global_load_dword v210, v[2:3], off offset:180
	global_load_dword v211, v[2:3], off offset:184
	global_load_dword v213, v[2:3], off offset:188
	global_load_dword v214, v[2:3], off offset:192
	global_load_dword v215, v[2:3], off offset:196
	global_load_dword v216, v[2:3], off offset:200
	global_load_dword v217, v[2:3], off offset:204
	global_load_dword v218, v[2:3], off offset:208
	global_load_dword v219, v[2:3], off offset:212
	global_load_dword v220, v[2:3], off offset:216
	global_load_dword v221, v[2:3], off offset:220
	global_load_dword v222, v[2:3], off offset:224
	global_load_dword v223, v[2:3], off offset:228
	global_load_dword v224, v[2:3], off offset:232
	global_load_dword v225, v[2:3], off offset:236
	global_load_dword v226, v[2:3], off offset:240
	global_load_dword v227, v[2:3], off offset:244
	global_load_dword v228, v[2:3], off offset:248
	s_waitcnt vmcnt(0)
	global_store_dword v[6:7], v4, off
	v_fmac_f32_e32 v100, v4, v164
	global_store_dword v[6:7], v100, off offset:512
	v_fmac_f32_e32 v101, v100, v165
	global_store_dword v[6:7], v101, off offset:1024
	v_fmac_f32_e32 v102, v101, v166
	global_store_dword v[6:7], v102, off offset:1536
	v_fmac_f32_e32 v103, v102, v167
	global_store_dword v[6:7], v103, off offset:2048
	v_fmac_f32_e32 v104, v103, v168
	global_store_dword v[6:7], v104, off offset:2560
	v_fmac_f32_e32 v105, v104, v169
	global_store_dword v[6:7], v105, off offset:3072
	v_fmac_f32_e32 v106, v105, v170
	global_store_dword v[6:7], v106, off offset:3584
	v_fmac_f32_e32 v107, v106, v171
	global_store_dword v[8:9], v107, off
	v_fmac_f32_e32 v108, v107, v172
	global_store_dword v[8:9], v108, off offset:512
	v_fmac_f32_e32 v109, v108, v173
	global_store_dword v[8:9], v109, off offset:1024
	v_fmac_f32_e32 v110, v109, v174
	global_store_dword v[8:9], v110, off offset:1536
	v_fmac_f32_e32 v111, v110, v175
	global_store_dword v[8:9], v111, off offset:2048
	v_fmac_f32_e32 v112, v111, v176
	global_store_dword v[8:9], v112, off offset:2560
	v_fmac_f32_e32 v113, v112, v177
	global_store_dword v[8:9], v113, off offset:3072
	v_fmac_f32_e32 v114, v113, v178
	global_store_dword v[8:9], v114, off offset:3584
	v_fmac_f32_e32 v115, v114, v179
	global_store_dword v[10:11], v115, off
	v_fmac_f32_e32 v116, v115, v180
	global_store_dword v[10:11], v116, off offset:512
	v_fmac_f32_e32 v117, v116, v181
	global_store_dword v[10:11], v117, off offset:1024
	v_fmac_f32_e32 v118, v117, v182
	global_store_dword v[10:11], v118, off offset:1536
	v_fmac_f32_e32 v119, v118, v183
	global_store_dword v[10:11], v119, off offset:2048
	v_fmac_f32_e32 v120, v119, v184
	global_store_dword v[10:11], v120, off offset:2560
	v_fmac_f32_e32 v121, v120, v185
	global_store_dword v[10:11], v121, off offset:3072
	v_fmac_f32_e32 v122, v121, v186
	global_store_dword v[10:11], v122, off offset:3584
	v_fmac_f32_e32 v123, v122, v187
	global_store_dword v[12:13], v123, off
	v_fmac_f32_e32 v124, v123, v188
	global_store_dword v[12:13], v124, off offset:512
	v_fmac_f32_e32 v125, v124, v189
	global_store_dword v[12:13], v125, off offset:1024
	v_fmac_f32_e32 v126, v125, v190
	global_store_dword v[12:13], v126, off offset:1536
	v_fmac_f32_e32 v127, v126, v191
	global_store_dword v[12:13], v127, off offset:2048
	v_fmac_f32_e32 v128, v127, v192
	global_store_dword v[12:13], v128, off offset:2560
	v_fmac_f32_e32 v129, v128, v193
	global_store_dword v[12:13], v129, off offset:3072
	v_fmac_f32_e32 v130, v129, v194
	global_store_dword v[12:13], v130, off offset:3584
	v_fmac_f32_e32 v131, v130, v195
	global_store_dword v[14:15], v131, off
	v_fmac_f32_e32 v132, v131, v196
	global_store_dword v[14:15], v132, off offset:512
	v_fmac_f32_e32 v133, v132, v197
	global_store_dword v[14:15], v133, off offset:1024
	v_fmac_f32_e32 v134, v133, v198
	global_store_dword v[14:15], v134, off offset:1536
	v_fmac_f32_e32 v135, v134, v199
	global_store_dword v[14:15], v135, off offset:2048
	v_fmac_f32_e32 v136, v135, v200
	global_store_dword v[14:15], v136, off offset:2560
	v_fmac_f32_e32 v137, v136, v201
	global_store_dword v[14:15], v137, off offset:3072
	v_fmac_f32_e32 v138, v137, v202
	global_store_dword v[14:15], v138, off offset:3584
	v_fmac_f32_e32 v139, v138, v203
	global_store_dword v[16:17], v139, off
	v_fmac_f32_e32 v140, v139, v204
	global_store_dword v[16:17], v140, off offset:512
	v_fmac_f32_e32 v141, v140, v205
	global_store_dword v[16:17], v141, off offset:1024
	v_fmac_f32_e32 v142, v141, v206
	global_store_dword v[16:17], v142, off offset:1536
	v_fmac_f32_e32 v143, v142, v207
	global_store_dword v[16:17], v143, off offset:2048
	v_fmac_f32_e32 v144, v143, v208
	global_store_dword v[16:17], v144, off offset:2560
	v_fmac_f32_e32 v145, v144, v209
	global_store_dword v[16:17], v145, off offset:3072
	v_fmac_f32_e32 v146, v145, v210
	global_store_dword v[16:17], v146, off offset:3584
	v_fmac_f32_e32 v147, v146, v211
	global_store_dword v[18:19], v147, off
	v_fmac_f32_e32 v148, v147, v213
	global_store_dword v[18:19], v148, off offset:512
	v_fmac_f32_e32 v149, v148, v214
	global_store_dword v[18:19], v149, off offset:1024
	v_fmac_f32_e32 v150, v149, v215
	global_store_dword v[18:19], v150, off offset:1536
	v_fmac_f32_e32 v151, v150, v216
	global_store_dword v[18:19], v151, off offset:2048
	v_fmac_f32_e32 v152, v151, v217
	global_store_dword v[18:19], v152, off offset:2560
	v_fmac_f32_e32 v153, v152, v218
	global_store_dword v[18:19], v153, off offset:3072
	v_fmac_f32_e32 v154, v153, v219
	global_store_dword v[18:19], v154, off offset:3584
	v_fmac_f32_e32 v155, v154, v220
	global_store_dword v[20:21], v155, off
	v_fmac_f32_e32 v156, v155, v221
	global_store_dword v[20:21], v156, off offset:512
	v_fmac_f32_e32 v157, v156, v222
	global_store_dword v[20:21], v157, off offset:1024
	v_fmac_f32_e32 v158, v157, v223
	global_store_dword v[20:21], v158, off offset:1536
	v_fmac_f32_e32 v159, v158, v224
	global_store_dword v[20:21], v159, off offset:2048
	v_fmac_f32_e32 v160, v159, v225
	global_store_dword v[20:21], v160, off offset:2560
	v_fmac_f32_e32 v161, v160, v226
	global_store_dword v[20:21], v161, off offset:3072
	v_fmac_f32_e32 v162, v161, v227
	global_store_dword v[20:21], v162, off offset:3584
	v_fmac_f32_e32 v163, v162, v228
	v_mov_b32_e32 v4, v163
	s_add_u32 s0, s0, 0x8000
	s_addc_u32 s1, s1, 0
	s_mov_b64 s[98:99], 256
	v_lshl_add_u64 v[2:3], v[2:3], 0, s[98:99]
	s_cmp_lg_u32 s0, 0x10000
	s_cbranch_scc1 .LBB0_708

.LBB0_774:
	s_or_b64 exec, exec, s[30:31]
	v_lshl_add_u64 v[18:19], s[62:63], 0, v[44:45]
	v_mov_b64_e32 v[20:21], s[40:41]
	v_mad_u64_u32 v[20:21], s[30:31], v18, s78, v[20:21]
	v_lshlrev_b64 v[2:3], 10, v[18:19]
	v_mov_b32_e32 v18, v21
	v_mad_u64_u32 v[18:19], s[30:31], v19, s78, v[18:19]
	v_mov_b32_e32 v21, v18
	s_lshl_b32 s30, s33, 9
	s_mov_b32 s31, s39
	v_lshl_add_u64 v[18:19], v[20:21], 0, s[30:31]
	v_lshlrev_b32_e32 v20, 1, v46
	v_mov_b32_e32 v21, v31
	v_lshl_add_u64 v[4:5], s[42:43], 0, v[2:3]
	s_lshl_b32 s38, s33, 8
	v_lshl_add_u64 v[2:3], s[44:45], 0, v[2:3]
	v_lshl_add_u64 v[18:19], v[18:19], 0, v[20:21]
	v_lshl_add_u64 v[4:5], v[4:5], 0, s[38:39]
	v_lshl_add_u64 v[2:3], v[2:3], 0, s[38:39]
	v_lshl_add_u64 v[22:23], v[18:19], 0, s[56:57]
	v_add_co_u32_e32 v18, vcc, s79, v18
	v_lshl_add_u64 v[6:7], v[4:5], 0, v[30:31]
	v_lshl_add_u64 v[14:15], v[2:3], 0, v[30:31]
	v_addc_co_u32_e32 v19, vcc, 0, v19, vcc
	global_load_dwordx4 v[2:5], v[6:7], off offset:16
	s_nop 0
	global_load_dwordx4 v[6:9], v[6:7], off
	s_nop 0
	global_load_dwordx4 v[10:13], v[14:15], off offset:16
	s_nop 0
	global_load_dwordx4 v[14:17], v[14:15], off
	s_nop 0
	global_load_dwordx4 v[18:21], v[18:19], off
	s_nop 0
	global_load_dwordx4 v[54:57], v[22:23], off offset:16
	global_load_dwordx4 v[58:61], v[22:23], off offset:32
	global_load_dwordx4 v[62:65], v[22:23], off offset:48
	v_add_u32_e32 v1, v73, v46
	s_waitcnt vmcnt(0)
	ds_write_b128 v1, v[6:9]
	ds_write_b128 v1, v[14:17] offset:17408
	ds_write_b128 v1, v[2:5] offset:16
	ds_write_b128 v1, v[10:13] offset:17424
	ds_write_b128 v86, v[18:21] offset:34816
	ds_write_b128 v86, v[54:57] offset:34832
	ds_write_b128 v86, v[58:61] offset:34848
	ds_write_b128 v86, v[62:65] offset:34864
	s_waitcnt lgkmcnt(0)
	s_barrier
	s_and_saveexec_b64 s[64:65], s[4:5]
	s_cbranch_execz .LBB0_786
	v_lshl_add_u32 v2, v24, 2, s77
	ds_read_b32 v1, v2
	s_waitcnt lgkmcnt(0)
	s_nop 1
	v_max_f32_dpp v1, v1, v1 row_shr:1 row_mask:0xf bank_mask:0xf
	s_nop 1
	v_max_f32_dpp v1, v1, v1 row_shr:2 row_mask:0xf bank_mask:0xf
	s_nop 1
	v_max_f32_dpp v1, v1, v1 row_shr:4 row_mask:0xf bank_mask:0xf
	s_nop 1
	v_max_f32_dpp v1, v1, v1 row_shr:8 row_mask:0xf bank_mask:0xf
	s_nop 1
	v_max_f32_dpp v1, v1, v1 row_bcast:15 row_mask:0xa bank_mask:0xf
	s_nop 1
	v_max_f32_dpp v1, v1, v1 row_bcast:31 row_mask:0xc bank_mask:0xf
	s_nop 1
.LBB0_785:
	v_max_f32_e32 v1, v1, v1
	v_max_f32_e32 v2, v0, v0
	v_max_f32_e32 v1, v2, v1
	v_sub_f32_e32 v0, v0, v1
	v_mul_f32_e32 v0, 0x3fb8aa3b, v0
	v_exp_f32_e32 v0, v0
	ds_write_b32 v79, v1
	ds_write_b32 v80, v0

.LBB0_808:
	v_add_u32_e32 v1, 0x11000, v85
	ds_read_b64 v[130:131], v1
	ds_read_b64 v[132:133], v1 offset:8
	ds_read_b64 v[134:135], v1 offset:16
	ds_read_b64 v[136:137], v1 offset:24
	ds_read_b64 v[138:139], v1 offset:32
	ds_read_b64 v[140:141], v1 offset:40
	ds_read_b64 v[142:143], v1 offset:48
	ds_read_b64 v[144:145], v1 offset:56
	ds_read_b64 v[146:147], v1 offset:64
	ds_read_b64 v[148:149], v1 offset:72
	ds_read_b64 v[150:151], v1 offset:80
	ds_read_b64 v[152:153], v1 offset:88
	ds_read_b64 v[154:155], v1 offset:96
	ds_read_b64 v[156:157], v1 offset:104
	ds_read_b64 v[158:159], v1 offset:112
	ds_read_b64 v[160:161], v1 offset:120
	s_waitcnt lgkmcnt(0)
	v_lshlrev_b32_e32 v1, 16, v130
	v_and_b32_e32 v2, 0xffff0000, v130
	v_add_f32_e32 v0, v0, v1
	v_lshlrev_b32_e32 v4, 16, v131
	v_add_f32_e32 v0, v0, v2
	v_and_b32_e32 v3, 0xffff0000, v131
	v_add_f32_e32 v0, v0, v4
	v_add_f32_e32 v0, v0, v3
	v_lshlrev_b32_e32 v1, 16, v132
	v_and_b32_e32 v2, 0xffff0000, v132
	v_add_f32_e32 v0, v0, v1
	v_lshlrev_b32_e32 v4, 16, v133
	v_add_f32_e32 v0, v0, v2
	v_and_b32_e32 v3, 0xffff0000, v133
	v_add_f32_e32 v0, v0, v4
	v_add_f32_e32 v0, v0, v3
	v_lshlrev_b32_e32 v1, 16, v134
	v_and_b32_e32 v2, 0xffff0000, v134
	v_add_f32_e32 v0, v0, v1
	v_lshlrev_b32_e32 v4, 16, v135
	v_add_f32_e32 v0, v0, v2
	v_and_b32_e32 v3, 0xffff0000, v135
	v_add_f32_e32 v0, v0, v4
	v_add_f32_e32 v0, v0, v3
	v_lshlrev_b32_e32 v1, 16, v136
	v_and_b32_e32 v2, 0xffff0000, v136
	v_add_f32_e32 v0, v0, v1
	v_lshlrev_b32_e32 v4, 16, v137
	v_add_f32_e32 v0, v0, v2
	v_and_b32_e32 v3, 0xffff0000, v137
	v_add_f32_e32 v0, v0, v4
	v_add_f32_e32 v0, v0, v3
	v_lshlrev_b32_e32 v1, 16, v138
	v_and_b32_e32 v2, 0xffff0000, v138
	v_add_f32_e32 v0, v0, v1
	v_lshlrev_b32_e32 v4, 16, v139
	v_add_f32_e32 v0, v0, v2
	v_and_b32_e32 v3, 0xffff0000, v139
	v_add_f32_e32 v0, v0, v4
	v_add_f32_e32 v0, v0, v3
	v_lshlrev_b32_e32 v1, 16, v140
	v_and_b32_e32 v2, 0xffff0000, v140
	v_add_f32_e32 v0, v0, v1
	v_lshlrev_b32_e32 v4, 16, v141
	v_add_f32_e32 v0, v0, v2
	v_and_b32_e32 v3, 0xffff0000, v141
	v_add_f32_e32 v0, v0, v4
	v_add_f32_e32 v0, v0, v3
	v_lshlrev_b32_e32 v1, 16, v142
	v_and_b32_e32 v2, 0xffff0000, v142
	v_add_f32_e32 v0, v0, v1
	v_lshlrev_b32_e32 v4, 16, v143
	v_add_f32_e32 v0, v0, v2
	v_and_b32_e32 v3, 0xffff0000, v143
	v_add_f32_e32 v0, v0, v4
	v_add_f32_e32 v0, v0, v3
	v_lshlrev_b32_e32 v1, 16, v144
	v_and_b32_e32 v2, 0xffff0000, v144
	v_add_f32_e32 v0, v0, v1
	v_lshlrev_b32_e32 v4, 16, v145
	v_add_f32_e32 v0, v0, v2
	v_and_b32_e32 v3, 0xffff0000, v145
	v_add_f32_e32 v0, v0, v4
	v_add_f32_e32 v0, v0, v3
	v_lshlrev_b32_e32 v1, 16, v146
	v_and_b32_e32 v2, 0xffff0000, v146
	v_add_f32_e32 v0, v0, v1
	v_lshlrev_b32_e32 v4, 16, v147
	v_add_f32_e32 v0, v0, v2
	v_and_b32_e32 v3, 0xffff0000, v147
	v_add_f32_e32 v0, v0, v4
	v_add_f32_e32 v0, v0, v3
	v_lshlrev_b32_e32 v1, 16, v148
	v_and_b32_e32 v2, 0xffff0000, v148
	v_add_f32_e32 v0, v0, v1
	v_lshlrev_b32_e32 v4, 16, v149
	v_add_f32_e32 v0, v0, v2
	v_and_b32_e32 v3, 0xffff0000, v149
	v_add_f32_e32 v0, v0, v4
	v_add_f32_e32 v0, v0, v3
	v_lshlrev_b32_e32 v1, 16, v150
	v_and_b32_e32 v2, 0xffff0000, v150
	v_add_f32_e32 v0, v0, v1
	v_lshlrev_b32_e32 v4, 16, v151
	v_add_f32_e32 v0, v0, v2
	v_and_b32_e32 v3, 0xffff0000, v151
	v_add_f32_e32 v0, v0, v4
	v_add_f32_e32 v0, v0, v3
	v_lshlrev_b32_e32 v1, 16, v152
	v_and_b32_e32 v2, 0xffff0000, v152
	v_add_f32_e32 v0, v0, v1
	v_lshlrev_b32_e32 v4, 16, v153
	v_add_f32_e32 v0, v0, v2
	v_and_b32_e32 v3, 0xffff0000, v153
	v_add_f32_e32 v0, v0, v4
	v_add_f32_e32 v0, v0, v3
	v_lshlrev_b32_e32 v1, 16, v154
	v_and_b32_e32 v2, 0xffff0000, v154
	v_add_f32_e32 v0, v0, v1
	v_lshlrev_b32_e32 v4, 16, v155
	v_add_f32_e32 v0, v0, v2
	v_and_b32_e32 v3, 0xffff0000, v155
	v_add_f32_e32 v0, v0, v4
	v_add_f32_e32 v0, v0, v3
	v_lshlrev_b32_e32 v1, 16, v156
	v_and_b32_e32 v2, 0xffff0000, v156
	v_add_f32_e32 v0, v0, v1
	v_lshlrev_b32_e32 v4, 16, v157
	v_add_f32_e32 v0, v0, v2
	v_and_b32_e32 v3, 0xffff0000, v157
	v_add_f32_e32 v0, v0, v4
	v_add_f32_e32 v0, v0, v3
	v_lshlrev_b32_e32 v1, 16, v158
	v_and_b32_e32 v2, 0xffff0000, v158
	v_add_f32_e32 v0, v0, v1
	v_lshlrev_b32_e32 v4, 16, v159
	v_add_f32_e32 v0, v0, v2
	v_and_b32_e32 v3, 0xffff0000, v159
	v_add_f32_e32 v0, v0, v4
	v_add_f32_e32 v0, v0, v3
	v_lshlrev_b32_e32 v1, 16, v160
	v_and_b32_e32 v2, 0xffff0000, v160
	v_add_f32_e32 v0, v0, v1
	v_lshlrev_b32_e32 v4, 16, v161
	v_add_f32_e32 v0, v0, v2
	v_and_b32_e32 v3, 0xffff0000, v161
	v_add_f32_e32 v0, v0, v4
	v_add_f32_e32 v0, v0, v3
	v_mov_b32_e32 v1, 0
	s_mov_b32 s33, 0
	s_mov_b32 s64, s81
.LBB0_810:
	s_add_i32 s65, s81, -12
	v_mov_b32_e32 v3, s65
	ds_read_b64 v[130:131], v81
	ds_read_b128 v[146:149], v3
	ds_read_b64 v[132:133], v81 offset:8
	ds_read_b128 v[150:153], v3 offset:16
	ds_read_b64 v[134:135], v81 offset:16
	ds_read_b128 v[154:157], v3 offset:32
	ds_read_b64 v[136:137], v81 offset:24
	ds_read_b128 v[158:161], v3 offset:48
	ds_read_b64 v[138:139], v81 offset:32
	ds_read_b128 v[162:165], v3 offset:64
	ds_read_b64 v[140:141], v81 offset:40
	ds_read_b128 v[166:169], v3 offset:80
	ds_read_b64 v[142:143], v81 offset:48
	ds_read_b128 v[170:173], v3 offset:96
	ds_read_b64 v[144:145], v81 offset:56
	ds_read_b128 v[174:177], v3 offset:112
	s_waitcnt lgkmcnt(0)
	v_lshlrev_b32_e32 v8, 16, v130
	v_and_b32_e32 v6, 0xffff0000, v130
	v_fmac_f32_e32 v1, v146, v8
	v_lshlrev_b32_e32 v9, 16, v131
	v_fmac_f32_e32 v1, v147, v6
	v_and_b32_e32 v7, 0xffff0000, v131
	v_fmac_f32_e32 v1, v148, v9
	v_fmac_f32_e32 v1, v149, v7
	v_lshlrev_b32_e32 v8, 16, v132
	v_and_b32_e32 v6, 0xffff0000, v132
	v_fmac_f32_e32 v1, v150, v8
	v_lshlrev_b32_e32 v9, 16, v133
	v_fmac_f32_e32 v1, v151, v6
	v_and_b32_e32 v7, 0xffff0000, v133
	v_fmac_f32_e32 v1, v152, v9
	v_fmac_f32_e32 v1, v153, v7
	v_lshlrev_b32_e32 v8, 16, v134
	v_and_b32_e32 v6, 0xffff0000, v134
	v_fmac_f32_e32 v1, v154, v8
	v_lshlrev_b32_e32 v9, 16, v135
	v_fmac_f32_e32 v1, v155, v6
	v_and_b32_e32 v7, 0xffff0000, v135
	v_fmac_f32_e32 v1, v156, v9
	v_fmac_f32_e32 v1, v157, v7
	v_lshlrev_b32_e32 v8, 16, v136
	v_and_b32_e32 v6, 0xffff0000, v136
	v_fmac_f32_e32 v1, v158, v8
	v_lshlrev_b32_e32 v9, 16, v137
	v_fmac_f32_e32 v1, v159, v6
	v_and_b32_e32 v7, 0xffff0000, v137
	v_fmac_f32_e32 v1, v160, v9
	v_fmac_f32_e32 v1, v161, v7
	v_lshlrev_b32_e32 v8, 16, v138
	v_and_b32_e32 v6, 0xffff0000, v138
	v_fmac_f32_e32 v1, v162, v8
	v_lshlrev_b32_e32 v9, 16, v139
	v_fmac_f32_e32 v1, v163, v6
	v_and_b32_e32 v7, 0xffff0000, v139
	v_fmac_f32_e32 v1, v164, v9
	v_fmac_f32_e32 v1, v165, v7
	v_lshlrev_b32_e32 v8, 16, v140
	v_and_b32_e32 v6, 0xffff0000, v140
	v_fmac_f32_e32 v1, v166, v8
	v_lshlrev_b32_e32 v9, 16, v141
	v_fmac_f32_e32 v1, v167, v6
	v_and_b32_e32 v7, 0xffff0000, v141
	v_fmac_f32_e32 v1, v168, v9
	v_fmac_f32_e32 v1, v169, v7
	v_lshlrev_b32_e32 v8, 16, v142
	v_and_b32_e32 v6, 0xffff0000, v142
	v_fmac_f32_e32 v1, v170, v8
	v_lshlrev_b32_e32 v9, 16, v143
	v_fmac_f32_e32 v1, v171, v6
	v_and_b32_e32 v7, 0xffff0000, v143
	v_fmac_f32_e32 v1, v172, v9
	v_fmac_f32_e32 v1, v173, v7
	v_lshlrev_b32_e32 v8, 16, v144
	v_and_b32_e32 v6, 0xffff0000, v144
	v_fmac_f32_e32 v1, v174, v8
	v_lshlrev_b32_e32 v9, 16, v145
	v_fmac_f32_e32 v1, v175, v6
	v_and_b32_e32 v7, 0xffff0000, v145
	v_fmac_f32_e32 v1, v176, v9
	v_fmac_f32_e32 v1, v177, v7
	ds_read_b64 v[130:131], v81 offset:64
	ds_read_b128 v[146:149], v3 offset:128
	ds_read_b64 v[132:133], v81 offset:72
	ds_read_b128 v[150:153], v3 offset:144
	ds_read_b64 v[134:135], v81 offset:80
	ds_read_b128 v[154:157], v3 offset:160
	ds_read_b64 v[136:137], v81 offset:88
	ds_read_b128 v[158:161], v3 offset:176
	ds_read_b64 v[138:139], v81 offset:96
	ds_read_b128 v[162:165], v3 offset:192
	ds_read_b64 v[140:141], v81 offset:104
	ds_read_b128 v[166:169], v3 offset:208
	ds_read_b64 v[142:143], v81 offset:112
	ds_read_b128 v[170:173], v3 offset:224
	ds_read_b64 v[144:145], v81 offset:120
	ds_read_b128 v[174:177], v3 offset:240
	s_waitcnt lgkmcnt(0)
	v_lshlrev_b32_e32 v8, 16, v130
	v_and_b32_e32 v6, 0xffff0000, v130
	v_fmac_f32_e32 v1, v146, v8
	v_lshlrev_b32_e32 v9, 16, v131
	v_fmac_f32_e32 v1, v147, v6
	v_and_b32_e32 v7, 0xffff0000, v131
	v_fmac_f32_e32 v1, v148, v9
	v_fmac_f32_e32 v1, v149, v7
	v_lshlrev_b32_e32 v8, 16, v132
	v_and_b32_e32 v6, 0xffff0000, v132
	v_fmac_f32_e32 v1, v150, v8
	v_lshlrev_b32_e32 v9, 16, v133
	v_fmac_f32_e32 v1, v151, v6
	v_and_b32_e32 v7, 0xffff0000, v133
	v_fmac_f32_e32 v1, v152, v9
	v_fmac_f32_e32 v1, v153, v7
	v_lshlrev_b32_e32 v8, 16, v134
	v_and_b32_e32 v6, 0xffff0000, v134
	v_fmac_f32_e32 v1, v154, v8
	v_lshlrev_b32_e32 v9, 16, v135
	v_fmac_f32_e32 v1, v155, v6
	v_and_b32_e32 v7, 0xffff0000, v135
	v_fmac_f32_e32 v1, v156, v9
	v_fmac_f32_e32 v1, v157, v7
	v_lshlrev_b32_e32 v8, 16, v136
	v_and_b32_e32 v6, 0xffff0000, v136
	v_fmac_f32_e32 v1, v158, v8
	v_lshlrev_b32_e32 v9, 16, v137
	v_fmac_f32_e32 v1, v159, v6
	v_and_b32_e32 v7, 0xffff0000, v137
	v_fmac_f32_e32 v1, v160, v9
	v_fmac_f32_e32 v1, v161, v7
	v_lshlrev_b32_e32 v8, 16, v138
	v_and_b32_e32 v6, 0xffff0000, v138
	v_fmac_f32_e32 v1, v162, v8
	v_lshlrev_b32_e32 v9, 16, v139
	v_fmac_f32_e32 v1, v163, v6
	v_and_b32_e32 v7, 0xffff0000, v139
	v_fmac_f32_e32 v1, v164, v9
	v_fmac_f32_e32 v1, v165, v7
	v_lshlrev_b32_e32 v8, 16, v140
	v_and_b32_e32 v6, 0xffff0000, v140
	v_fmac_f32_e32 v1, v166, v8
	v_lshlrev_b32_e32 v9, 16, v141
	v_fmac_f32_e32 v1, v167, v6
	v_and_b32_e32 v7, 0xffff0000, v141
	v_fmac_f32_e32 v1, v168, v9
	v_fmac_f32_e32 v1, v169, v7
	v_lshlrev_b32_e32 v8, 16, v142
	v_and_b32_e32 v6, 0xffff0000, v142
	v_fmac_f32_e32 v1, v170, v8
	v_lshlrev_b32_e32 v9, 16, v143
	v_fmac_f32_e32 v1, v171, v6
	v_and_b32_e32 v7, 0xffff0000, v143
	v_fmac_f32_e32 v1, v172, v9
	v_fmac_f32_e32 v1, v173, v7
	v_lshlrev_b32_e32 v8, 16, v144
	v_and_b32_e32 v6, 0xffff0000, v144
	v_fmac_f32_e32 v1, v174, v8
	v_lshlrev_b32_e32 v9, 16, v145
	v_fmac_f32_e32 v1, v175, v6
	v_and_b32_e32 v7, 0xffff0000, v145
	v_fmac_f32_e32 v1, v176, v9
	v_fmac_f32_e32 v1, v177, v7
	ds_read_b64 v[130:131], v81 offset:128
	ds_read_b128 v[146:149], v3 offset:256
	ds_read_b64 v[132:133], v81 offset:136
	ds_read_b128 v[150:153], v3 offset:272
	ds_read_b64 v[134:135], v81 offset:144
	ds_read_b128 v[154:157], v3 offset:288
	ds_read_b64 v[136:137], v81 offset:152
	ds_read_b128 v[158:161], v3 offset:304
	ds_read_b64 v[138:139], v81 offset:160
	ds_read_b128 v[162:165], v3 offset:320
	ds_read_b64 v[140:141], v81 offset:168
	ds_read_b128 v[166:169], v3 offset:336
	ds_read_b64 v[142:143], v81 offset:176
	ds_read_b128 v[170:173], v3 offset:352
	ds_read_b64 v[144:145], v81 offset:184
	ds_read_b128 v[174:177], v3 offset:368
	s_waitcnt lgkmcnt(0)
	v_lshlrev_b32_e32 v8, 16, v130
	v_and_b32_e32 v6, 0xffff0000, v130
	v_fmac_f32_e32 v1, v146, v8
	v_lshlrev_b32_e32 v9, 16, v131
	v_fmac_f32_e32 v1, v147, v6
	v_and_b32_e32 v7, 0xffff0000, v131
	v_fmac_f32_e32 v1, v148, v9
	v_fmac_f32_e32 v1, v149, v7
	v_lshlrev_b32_e32 v8, 16, v132
	v_and_b32_e32 v6, 0xffff0000, v132
	v_fmac_f32_e32 v1, v150, v8
	v_lshlrev_b32_e32 v9, 16, v133
	v_fmac_f32_e32 v1, v151, v6
	v_and_b32_e32 v7, 0xffff0000, v133
	v_fmac_f32_e32 v1, v152, v9
	v_fmac_f32_e32 v1, v153, v7
	v_lshlrev_b32_e32 v8, 16, v134
	v_and_b32_e32 v6, 0xffff0000, v134
	v_fmac_f32_e32 v1, v154, v8
	v_lshlrev_b32_e32 v9, 16, v135
	v_fmac_f32_e32 v1, v155, v6
	v_and_b32_e32 v7, 0xffff0000, v135
	v_fmac_f32_e32 v1, v156, v9
	v_fmac_f32_e32 v1, v157, v7
	v_lshlrev_b32_e32 v8, 16, v136
	v_and_b32_e32 v6, 0xffff0000, v136
	v_fmac_f32_e32 v1, v158, v8
	v_lshlrev_b32_e32 v9, 16, v137
	v_fmac_f32_e32 v1, v159, v6
	v_and_b32_e32 v7, 0xffff0000, v137
	v_fmac_f32_e32 v1, v160, v9
	v_fmac_f32_e32 v1, v161, v7
	v_lshlrev_b32_e32 v8, 16, v138
	v_and_b32_e32 v6, 0xffff0000, v138
	v_fmac_f32_e32 v1, v162, v8
	v_lshlrev_b32_e32 v9, 16, v139
	v_fmac_f32_e32 v1, v163, v6
	v_and_b32_e32 v7, 0xffff0000, v139
	v_fmac_f32_e32 v1, v164, v9
	v_fmac_f32_e32 v1, v165, v7
	v_lshlrev_b32_e32 v8, 16, v140
	v_and_b32_e32 v6, 0xffff0000, v140
	v_fmac_f32_e32 v1, v166, v8
	v_lshlrev_b32_e32 v9, 16, v141
	v_fmac_f32_e32 v1, v167, v6
	v_and_b32_e32 v7, 0xffff0000, v141
	v_fmac_f32_e32 v1, v168, v9
	v_fmac_f32_e32 v1, v169, v7
	v_lshlrev_b32_e32 v8, 16, v142
	v_and_b32_e32 v6, 0xffff0000, v142
	v_fmac_f32_e32 v1, v170, v8
	v_lshlrev_b32_e32 v9, 16, v143
	v_fmac_f32_e32 v1, v171, v6
	v_and_b32_e32 v7, 0xffff0000, v143
	v_fmac_f32_e32 v1, v172, v9
	v_fmac_f32_e32 v1, v173, v7
	v_lshlrev_b32_e32 v8, 16, v144
	v_and_b32_e32 v6, 0xffff0000, v144
	v_fmac_f32_e32 v1, v174, v8
	v_lshlrev_b32_e32 v9, 16, v145
	v_fmac_f32_e32 v1, v175, v6
	v_and_b32_e32 v7, 0xffff0000, v145
	v_fmac_f32_e32 v1, v176, v9
	v_fmac_f32_e32 v1, v177, v7
	ds_read_b64 v[130:131], v81 offset:192
	ds_read_b128 v[146:149], v3 offset:384
	ds_read_b64 v[132:133], v81 offset:200
	ds_read_b128 v[150:153], v3 offset:400
	ds_read_b64 v[134:135], v81 offset:208
	ds_read_b128 v[154:157], v3 offset:416
	ds_read_b64 v[136:137], v81 offset:216
	ds_read_b128 v[158:161], v3 offset:432
	ds_read_b64 v[138:139], v81 offset:224
	ds_read_b128 v[162:165], v3 offset:448
	ds_read_b64 v[140:141], v81 offset:232
	ds_read_b128 v[166:169], v3 offset:464
	ds_read_b64 v[142:143], v81 offset:240
	ds_read_b128 v[170:173], v3 offset:480
	ds_read_b64 v[144:145], v81 offset:248
	ds_read_b128 v[174:177], v3 offset:496
	s_waitcnt lgkmcnt(0)
	v_lshlrev_b32_e32 v8, 16, v130
	v_and_b32_e32 v6, 0xffff0000, v130
	v_fmac_f32_e32 v1, v146, v8
	v_lshlrev_b32_e32 v9, 16, v131
	v_fmac_f32_e32 v1, v147, v6
	v_and_b32_e32 v7, 0xffff0000, v131
	v_fmac_f32_e32 v1, v148, v9
	v_fmac_f32_e32 v1, v149, v7
	v_lshlrev_b32_e32 v8, 16, v132
	v_and_b32_e32 v6, 0xffff0000, v132
	v_fmac_f32_e32 v1, v150, v8
	v_lshlrev_b32_e32 v9, 16, v133
	v_fmac_f32_e32 v1, v151, v6
	v_and_b32_e32 v7, 0xffff0000, v133
	v_fmac_f32_e32 v1, v152, v9
	v_fmac_f32_e32 v1, v153, v7
	v_lshlrev_b32_e32 v8, 16, v134
	v_and_b32_e32 v6, 0xffff0000, v134
	v_fmac_f32_e32 v1, v154, v8
	v_lshlrev_b32_e32 v9, 16, v135
	v_fmac_f32_e32 v1, v155, v6
	v_and_b32_e32 v7, 0xffff0000, v135
	v_fmac_f32_e32 v1, v156, v9
	v_fmac_f32_e32 v1, v157, v7
	v_lshlrev_b32_e32 v8, 16, v136
	v_and_b32_e32 v6, 0xffff0000, v136
	v_fmac_f32_e32 v1, v158, v8
	v_lshlrev_b32_e32 v9, 16, v137
	v_fmac_f32_e32 v1, v159, v6
	v_and_b32_e32 v7, 0xffff0000, v137
	v_fmac_f32_e32 v1, v160, v9
	v_fmac_f32_e32 v1, v161, v7
	v_lshlrev_b32_e32 v8, 16, v138
	v_and_b32_e32 v6, 0xffff0000, v138
	v_fmac_f32_e32 v1, v162, v8
	v_lshlrev_b32_e32 v9, 16, v139
	v_fmac_f32_e32 v1, v163, v6
	v_and_b32_e32 v7, 0xffff0000, v139
	v_fmac_f32_e32 v1, v164, v9
	v_fmac_f32_e32 v1, v165, v7
	v_lshlrev_b32_e32 v8, 16, v140
	v_and_b32_e32 v6, 0xffff0000, v140
	v_fmac_f32_e32 v1, v166, v8
	v_lshlrev_b32_e32 v9, 16, v141
	v_fmac_f32_e32 v1, v167, v6
	v_and_b32_e32 v7, 0xffff0000, v141
	v_fmac_f32_e32 v1, v168, v9
	v_fmac_f32_e32 v1, v169, v7
	v_lshlrev_b32_e32 v8, 16, v142
	v_and_b32_e32 v6, 0xffff0000, v142
	v_fmac_f32_e32 v1, v170, v8
	v_lshlrev_b32_e32 v9, 16, v143
	v_fmac_f32_e32 v1, v171, v6
	v_and_b32_e32 v7, 0xffff0000, v143
	v_fmac_f32_e32 v1, v172, v9
	v_fmac_f32_e32 v1, v173, v7
	v_lshlrev_b32_e32 v8, 16, v144
	v_and_b32_e32 v6, 0xffff0000, v144
	v_fmac_f32_e32 v1, v174, v8
	v_lshlrev_b32_e32 v9, 16, v145
	v_fmac_f32_e32 v1, v175, v6
	v_and_b32_e32 v7, 0xffff0000, v145
	v_fmac_f32_e32 v1, v176, v9
	v_fmac_f32_e32 v1, v177, v7
	ds_read_b32 v2, v76
	ds_read_b32 v3, v79
	ds_read_b32 v4, v80
	s_waitcnt lgkmcnt(1)
	v_add_f32_e32 v2, v2, v3
	v_mul_f32_e32 v2, 0xbfb8aa3b, v2
	v_exp_f32_e32 v2, v2
	s_waitcnt lgkmcnt(0)
	v_fmac_f32_e32 v0, v1, v4
	v_max_f32_e64 v0, |v0|, v2
	v_rcp_f32_e32 v0, v0
	ds_write_b32 v82, v0
